# v74 + same wave-priority split in the cross-attention phase
# speedup vs baseline: 1.0040x; 1.0040x over previous
; template <bool MOBA>
; __device__ __forceinline__ void attn_unit(LAS unsigned char* lds, const bf16_t* Qp, int ldq, const bf16_t* Kp, const bf16_t* Vp, int ldkv, bf16_t* Op, int ldo, int qt, const float* kmean, const float* relb, const int tid) {
;     ...
;         for (int s = 0; s < 4; ++s) qf[s] = *(const bf16x8*)(Qp + (size_t)(w * 16 + l15) * ldq + quad * 8 + 32 * s);
;     }
;     f32x4 oacc[8]; float mrow = -INFINITY, lrow = 0.f;
; #pragma unroll
;     for (int n = 0; n < 8; ++n) oacc[n] = (f32x4){0.f, 0.f, 0.f, 0.f};
;     const int nhalf = MOBA ? own * 2 + (qt & 1) + 1 : 2;
;     const float sc2 = 0.08838834764831845f * L2E;
;     u32x4 kreg[4], vreg[4];
; #pragma unroll
;     for (int i = 0; i < 4; ++i) { const int id = tid + 512 * i, r = id >> 4, c = id & 15; kreg[i] = *(const u32x4*)(Kp + (size_t)r * ldkv + c * 8); vreg[i] = *(const u32x4*)(Vp + (size_t)r * ldkv + c * 8); }
; __global__ void __launch_bounds__(NTHREADS, 2) mega(Args a) {
;     ...
;     if (lo <= P_XATT && P_XATT < hi) {
;         PHASE_HEAD
;         for (int u = bx; u < 512; u += G) { const int qt = u & 31, bh = u >> 5, b = bh >> 2, xh = bh & 3;
;             const bf16_t* kv = (const bf16_t*)(ws + WS_KVX) + (size_t)(b * 256) * 1024 + xh * 128;
;             attn_unit<false>(lds, (const bf16_t*)(ws + WS_QX) + (size_t)(b * SEQ + qt * 128) * 512 + xh * 128, 512, kv, kv + 512, 1024, (bf16_t*)(ws + WS_OX) + (size_t)(b * SEQ + qt * 128) * 512 + xh * 128, 512, qt, nullptr, nullptr, tid); }
.LBB0_1736:
	s_cmp_lt_i32 s64, 11
	s_cselect_b64 s[0:1], -1, 0
	s_cmp_gt_i32 s65, 10
	s_cselect_b64 s[2:3], -1, 0
	s_and_b64 s[2:3], s[0:1], s[2:3]
	s_andn2_b64 vcc, exec, s[2:3]
	s_cbranch_vccnz .LBB0_1747
	s_mov_b32 s2, 0
	v_mov_b32_e32 v148, v205
	s_cmpk_gt_i32 s66, 0x1ff
	s_cbranch_scc1 .LBB0_1747
	v_readfirstlane_b32 s32, v205
	s_cmpk_lt_u32 s32, 0x100
	s_cbranch_scc0 .Lprio2_skip
	s_setprio 2
.Lprio2_skip:
	v_readlane_b32 s4, v253, 0
	v_readlane_b32 s5, v253, 1
	s_load_dwordx2 s[4:5], s[4:5], 0xd8
	s_ashr_i32 s3, s2, 31
	v_add_u32_e32 v5, 0x200, v148
	v_ashrrev_i32_e32 v8, 4, v5
	v_bfe_u32 v1, v148, 4, 2
	s_waitcnt lgkmcnt(0)
	s_add_u32 s4, s4, s2
	s_addc_u32 s5, s5, s3
	s_add_u32 s2, s4, 0x2400000
	s_addc_u32 s3, s5, 0
	s_add_u32 s8, s4, 0x18500000
	v_ashrrev_i32_e32 v6, 4, v148
	v_ashrrev_i32_e32 v9, 31, v8
	v_add_u32_e32 v5, 0x400, v148
	s_addc_u32 s9, s5, 0
	v_ashrrev_i32_e32 v7, 31, v6
	v_lshlrev_b64 v[118:119], 10, v[8:9]
	v_ashrrev_i32_e32 v10, 4, v5
	v_add_u32_e32 v5, 0x600, v148
	v_bfe_u32 v9, v148, 2, 2
	v_lshlrev_b32_e32 v14, 2, v1
	s_add_u32 s10, s4, 0x19500000
	v_lshlrev_b32_e32 v2, 3, v1
	v_lshlrev_b32_e32 v3, 3, v148
	v_lshlrev_b64 v[116:117], 10, v[6:7]
	v_ashrrev_i32_e32 v12, 4, v5
	v_lshlrev_b32_e32 v5, 4, v148
	v_lshl_add_u32 v7, v1, 4, 0
	v_or_b32_e32 v1, v14, v9
	s_addc_u32 s11, s5, 0
	v_and_b32_e32 v149, 15, v148
	v_and_b32_e32 v4, 0x78, v3
	v_ashrrev_i32_e32 v11, 31, v10
	v_ashrrev_i32_e32 v13, 31, v12
	v_and_b32_e32 v5, 0xf0, v5
	v_and_b32_e32 v3, 24, v3
	s_movk_i32 s4, 0x110
	s_movk_i32 s5, 0x120
	v_mul_u32_u24_e32 v1, 0x120, v1
	v_mov_b32_e32 v0, 0
	v_lshlrev_b64 v[120:121], 10, v[10:11]
	v_lshlrev_b64 v[122:123], 10, v[12:13]
	v_add_u32_e32 v5, 0, v5
	v_mul_lo_u32 v9, v6, s4
	v_mul_lo_u32 v6, v6, s5
	v_mul_lo_u32 v11, v8, s4
	v_mul_lo_u32 v8, v8, s5
	v_mul_lo_u32 v13, v10, s4
	v_mul_lo_u32 v10, v10, s5
	v_mul_lo_u32 v15, v12, s4
	v_mul_lo_u32 v12, v12, s5
	s_mov_b64 s[4:5], 0x20000
	v_mul_u32_u24_e32 v16, 0x110, v149
	v_add3_u32 v150, 0, v3, v1
	v_lshl_add_u64 v[124:125], v[116:117], 0, s[4:5]
	v_lshl_add_u64 v[126:127], v[118:119], 0, s[4:5]
	v_lshl_add_u64 v[128:129], v[120:121], 0, s[4:5]
	v_lshl_add_u64 v[130:131], v[122:123], 0, s[4:5]
	v_add_u32_e32 v151, 0x8800, v150
	v_lshlrev_b32_e32 v132, 1, v2
	v_mov_b32_e32 v133, v0
	v_lshlrev_b32_e32 v134, 1, v4
	v_mov_b32_e32 v135, v0
	v_add_u32_e32 v152, v5, v9
	v_add_u32_e32 v153, v5, v6
	v_add_u32_e32 v154, v5, v11
	v_add_u32_e32 v155, v5, v8
	v_add_u32_e32 v156, v5, v13
	v_add_u32_e32 v157, v5, v10
	v_add_u32_e32 v158, v5, v15
	v_add_u32_e32 v159, v5, v12
	v_add_u32_e32 v160, v7, v16
	s_mov_b32 s12, 0xff800000
	s_mov_b32 s13, 0x3e0293ee
	v_lshlrev_b32_e32 v136, 1, v14
	v_mbcnt_hi_u32_b32 v161, -1, v226
	s_mov_b32 s14, s66
	s_branch .LBB0_1740

; __device__ __forceinline__ unsigned xb_add(unsigned* p, unsigned v) { return __hip_atomic_fetch_add(p, v, __ATOMIC_RELAXED, __HIP_MEMORY_SCOPE_AGENT); }
; __device__ __forceinline__ void xcd_barrier(const XcdBarrier& b) {
;     asm volatile("s_waitcnt vmcnt(0)" ::: "memory");
;     __syncthreads();
;     if (threadIdx.x == 0) {
;         unsigned* bar = b.bar;
;         __builtin_amdgcn_s_waitcnt(0);
;         unsigned nloc = b.st[0], nx = b.st[1];
;         if (nloc == 0u) { xcd_barrier_complete(bar, b.x, nloc, nx); b.st[0] = nloc; b.st[1] = nx; }
;         const unsigned old = xb_add(&bar[XB_XSUB(b.x)], 1u);
.LBB0_1747:
	s_cmp_gt_i32 s65, 11
	s_cselect_b64 s[2:3], -1, 0
	s_and_b64 s[0:1], s[0:1], s[2:3]
	s_andn2_b64 vcc, exec, s[0:1]
	s_cbranch_vccnz .LBB0_1815
	s_cmpk_lt_u32 s65, 0x3e9
	s_mov_b64 s[0:1], -1
	s_cbranch_scc0 .LBB0_1802
	s_setprio 0
	s_waitcnt vmcnt(0)
	s_waitcnt lgkmcnt(0)
	s_barrier
	s_mov_b64 s[0:1], exec
	v_readlane_b32 s2, v253, 9
	v_readlane_b32 s3, v253, 10
	s_and_b64 s[2:3], s[0:1], s[2:3]
	s_mov_b64 exec, s[2:3]
	s_cbranch_execz .LBB0_1801
	s_add_i32 s2, 0, 0x27500
	v_mov_b32_e32 v0, s2
	s_waitcnt vmcnt(0) expcnt(0) lgkmcnt(0)
	ds_read_b32 v2, v0
	s_add_i32 s2, 0, 0x27504
	v_mov_b32_e32 v0, s2
	ds_read_b32 v0, v0
	s_waitcnt lgkmcnt(1)
	v_cmp_ne_u32_e32 vcc, 0, v2
	s_cbranch_vccnz .LBB0_1765
	v_readlane_b32 s4, v253, 2
	v_readlane_b32 s5, v253, 3
	v_readlane_b32 s10, v253, 6
	s_load_dwordx2 s[2:3], s[4:5], 0x4
	v_readlane_b32 s11, v253, 7
	s_add_u32 s4, s10, 0x1000
	s_addc_u32 s5, s11, 0
	s_add_u32 s6, s10, 0x1100
	s_addc_u32 s7, s11, 0
	s_add_u32 s8, s10, 0x1200
	s_addc_u32 s9, s11, 0
	s_waitcnt lgkmcnt(0)
	s_mul_i32 s2, s2, s69
	s_add_u32 s10, s10, 0x1300
	s_mul_i32 s2, s2, s3
	s_addc_u32 s11, s11, 0
	s_mov_b32 s3, 1
	v_mov_b32_e32 v16, 0
	s_branch .LBB0_1753
